# speedup vs baseline: 1.0039x; 1.0021x over previous
.LBB0_742:
	s_or_b64 exec, exec, s[0:1]
	s_waitcnt vmcnt(40)
	v_mul_f32_e32 v35, v44, v40
	s_waitcnt lgkmcnt(0)
	v_mul_f32_e32 v37, 0x3fb8aa3b, v35
	s_mov_b32 s0, 0x3fb8aa3b
	v_fma_f32 v39, v35, s0, -v37
	v_rndne_f32_e32 v40, v37
	v_fmac_f32_e32 v39, 0x32a5705f, v35
	v_sub_f32_e32 v37, v37, v40
	v_add_f32_e32 v37, v37, v39
	v_exp_f32_e32 v37, v37
	v_cvt_i32_f32_e32 v39, v40
	s_mov_b32 s0, 0xc2ce8ed0
	v_cmp_ngt_f32_e32 vcc, s0, v35
	s_mov_b32 s0, 0x42b17218
	v_ldexp_f32 v37, v37, v39
	v_cndmask_b32_e32 v37, 0, v37, vcc
	v_cmp_nlt_f32_e32 vcc, s0, v35
	s_brev_b32 s0, 1
	v_lshlrev_b32_e32 v126, 5, v43
	v_cndmask_b32_e32 v35, v217, v37, vcc
	v_mul_f32_e32 v37, v48, v48
	v_fmamk_f32 v39, v37, 0xb94c1982, v206
	v_fmaak_f32 v39, v37, v39, 0xbe2aaa9d
	v_mul_f32_e32 v39, v37, v39
	v_fmac_f32_e32 v48, v48, v39
	v_fmamk_f32 v39, v37, 0x37d75334, v207
	v_fmaak_f32 v39, v37, v39, 0x3d2aabf7
	v_fmaak_f32 v39, v37, v39, 0xbf000004
	v_fma_f32 v37, v37, v39, 1.0
	v_and_b32_e32 v39, 1, v47
	v_cmp_eq_u32_e32 vcc, 0, v39
	v_lshlrev_b32_e32 v39, 30, v47
	v_mov_b32_e32 v127, v96
	v_cndmask_b32_e64 v37, -v48, v37, vcc
	v_bitop3_b32 v37, v39, v37, s0 bitop3:0x6c
	v_mul_f32_e32 v39, v50, v50
	v_fmamk_f32 v47, v39, 0xb94c1982, v206
	v_fmaak_f32 v47, v39, v47, 0xbe2aaa9d
	v_mul_f32_e32 v47, v39, v47
	v_fmac_f32_e32 v50, v50, v47
	v_fmamk_f32 v47, v39, 0x37d75334, v207
	v_fmaak_f32 v47, v39, v47, 0x3d2aabf7
	v_fmaak_f32 v47, v39, v47, 0xbf000004
	s_movk_i32 s0, 0x1f8
	v_fma_f32 v39, v39, v47, 1.0
	v_and_b32_e32 v47, 1, v49
	v_cmp_class_f32_e64 vcc, v42, s0
	v_cmp_eq_u32_e64 s[0:1], 0, v47
	v_lshlrev_b32_e32 v47, 30, v49
	v_and_b32_e32 v47, 0x80000000, v47
	v_xor_b32_e32 v42, v46, v42
	v_cndmask_b32_e64 v39, v39, v50, s[0:1]
	v_xor_b32_e32 v42, v42, v47
	v_xor_b32_e32 v39, v42, v39
	v_cndmask_b32_e32 v39, v220, v39, vcc
	v_cndmask_b32_e32 v37, v220, v37, vcc
	v_mul_f32_e32 v42, v35, v39
	v_fma_f32 v48, v35, v37, -1.0
	v_mov_b32_e32 v49, v42
	v_mov_b32_e32 v50, v45
	v_pk_mul_f32 v[46:47], v[44:45], v[44:45]
	v_pk_mul_f32 v[50:51], v[50:51], v[48:49] op_sel:[0,1] op_sel_hi:[0,0]
	v_pk_fma_f32 v[52:53], v[44:45], v[48:49], v[50:51]
	v_pk_fma_f32 v[44:45], v[44:45], v[48:49], v[50:51] op_sel_hi:[0,1,1] neg_lo:[0,0,1] neg_hi:[0,0,1]
	v_pk_add_f32 v[46:47], v[46:47], v[46:47] op_sel:[0,1] op_sel_hi:[0,1]
	v_mul_f32_e32 v40, v35, v37
	v_div_scale_f32 v35, s[0:1], v47, v47, v45
	v_rcp_f32_e32 v37, v35
	s_mov_b32 s14, 0
	v_cmp_gt_u32_e64 s[6:7], 16, v41
	v_mov_b32_e32 v43, v42
	v_fma_f32 v39, -v35, v37, 1.0
	v_fmac_f32_e32 v37, v39, v37
	v_div_scale_f32 v39, vcc, v45, v47, v45
	v_mul_f32_e32 v44, v39, v37
	v_fma_f32 v48, -v35, v44, v39
	v_fmac_f32_e32 v44, v48, v37
	v_fma_f32 v35, -v35, v44, v39
	v_div_fmas_f32 v35, v35, v37, v44
	v_div_fixup_f32 v83, v35, v47, v45
	v_div_scale_f32 v35, s[0:1], v46, v46, v52
	v_rcp_f32_e32 v37, v35
	s_movk_i32 s0, 0x2600
	s_mov_b64 s[8:9], 0
	s_waitcnt vmcnt(6)
	v_xor_b32_e32 v97, 0x80000000, v119
	v_fma_f32 v39, -v35, v37, 1.0
	v_fmac_f32_e32 v37, v39, v37
	v_div_scale_f32 v39, vcc, v52, v46, v52
	v_mul_f32_e32 v44, v39, v37
	v_fma_f32 v45, -v35, v44, v39
	v_fmac_f32_e32 v44, v45, v37
	v_fma_f32 v35, -v35, v44, v39
	v_div_fmas_f32 v35, v35, v37, v44
	v_div_fixup_f32 v82, v35, v46, v52
	v_pk_mul_f32 v[64:65], v[82:83], v[12:13] op_sel:[1,0] op_sel_hi:[0,1]
	v_pk_mul_f32 v[60:61], v[82:83], v[12:13]
	v_pk_mul_f32 v[48:49], v[28:29], v[82:83] op_sel:[0,1] op_sel_hi:[1,0]
	v_pk_mul_f32 v[44:45], v[28:29], v[82:83]
	v_pk_mul_f32 v[56:57], v[82:83], v[20:21] op_sel:[1,0] op_sel_hi:[0,1]
	v_pk_mul_f32 v[52:53], v[82:83], v[20:21]
	v_pk_fma_f32 v[12:13], v[82:83], v[8:9], v[60:61] op_sel:[0,1,1] op_sel_hi:[1,0,0] neg_lo:[0,0,1] neg_hi:[0,0,1]
	v_pk_fma_f32 v[60:61], v[82:83], v[8:9], v[60:61] op_sel:[0,1,1] op_sel_hi:[1,0,0]
	v_pk_fma_f32 v[62:63], v[82:83], v[8:9], v[64:65] neg_lo:[0,0,1] neg_hi:[0,0,1]
	v_pk_fma_f32 v[8:9], v[82:83], v[8:9], v[64:65]
	v_pk_mul_f32 v[74:75], v[82:83], v[4:5] op_sel:[1,0] op_sel_hi:[0,1]
	v_pk_mul_f32 v[4:5], v[82:83], v[4:5]
	v_pk_fma_f32 v[28:29], v[24:25], v[82:83], v[44:45] op_sel:[1,0,1] op_sel_hi:[0,1,0] neg_lo:[0,0,1] neg_hi:[0,0,1]
	v_pk_fma_f32 v[44:45], v[24:25], v[82:83], v[44:45] op_sel:[1,0,1] op_sel_hi:[0,1,0]
	v_pk_fma_f32 v[46:47], v[24:25], v[82:83], v[48:49] neg_lo:[0,0,1] neg_hi:[0,0,1]
	v_pk_fma_f32 v[24:25], v[24:25], v[82:83], v[48:49]
	v_pk_fma_f32 v[20:21], v[16:17], v[82:83], v[52:53] op_sel:[1,0,1] op_sel_hi:[0,1,0] neg_lo:[0,0,1] neg_hi:[0,0,1]
	v_pk_fma_f32 v[52:53], v[16:17], v[82:83], v[52:53] op_sel:[1,0,1] op_sel_hi:[0,1,0]
	v_pk_fma_f32 v[54:55], v[16:17], v[82:83], v[56:57] neg_lo:[0,0,1] neg_hi:[0,0,1]
	v_pk_fma_f32 v[16:17], v[16:17], v[82:83], v[56:57]
	v_mov_b32_e32 v8, v15
	v_pk_fma_f32 v[68:69], v[82:83], v[0:1], v[4:5] op_sel:[0,1,1] op_sel_hi:[1,0,0] neg_lo:[0,0,1] neg_hi:[0,0,1]
	v_pk_fma_f32 v[70:71], v[82:83], v[0:1], v[4:5] op_sel:[0,1,1] op_sel_hi:[1,0,0]
	v_pk_fma_f32 v[72:73], v[82:83], v[0:1], v[74:75] neg_lo:[0,0,1] neg_hi:[0,0,1]
	v_pk_fma_f32 v[74:75], v[82:83], v[0:1], v[74:75]
	v_pk_mul_f32 v[0:1], v[82:83], v[6:7] op_sel:[1,0] op_sel_hi:[0,0]
	v_mov_b32_e32 v24, v31
	v_mov_b32_e32 v16, v23
	v_pk_mul_f32 v[66:67], v[82:83], v[14:15] op_sel:[1,0] op_sel_hi:[0,0]
	v_pk_mul_f32 v[14:15], v[82:83], v[8:9] op_sel:[1,0] op_sel_hi:[0,0]
	v_mov_b32_e32 v8, v11
	v_pk_fma_f32 v[76:77], v[82:83], v[2:3], v[0:1] op_sel_hi:[1,0,1] neg_lo:[0,0,1] neg_hi:[0,0,1]
	v_pk_fma_f32 v[78:79], v[82:83], v[2:3], v[0:1] op_sel_hi:[1,0,1]
	v_mov_b32_e32 v0, v7
	v_pk_mul_f32 v[50:51], v[30:31], v[82:83] op_sel:[0,1] op_sel_hi:[0,0]
	v_pk_mul_f32 v[30:31], v[24:25], v[82:83] op_sel:[0,1] op_sel_hi:[0,0]
	v_mov_b32_e32 v24, v27
	v_pk_mul_f32 v[58:59], v[82:83], v[22:23] op_sel:[1,0] op_sel_hi:[0,0]
	v_pk_mul_f32 v[22:23], v[82:83], v[16:17] op_sel:[1,0] op_sel_hi:[0,0]
	v_mov_b32_e32 v16, v19
	v_pk_fma_f32 v[64:65], v[82:83], v[10:11], v[66:67] op_sel_hi:[1,0,1] neg_lo:[0,0,1] neg_hi:[0,0,1]
	v_pk_fma_f32 v[66:67], v[82:83], v[10:11], v[66:67] op_sel_hi:[1,0,1]
	v_pk_fma_f32 v[10:11], v[82:83], v[8:9], v[14:15] op_sel_hi:[1,0,1] neg_lo:[0,0,1] neg_hi:[0,0,1]
	v_pk_fma_f32 v[14:15], v[82:83], v[8:9], v[14:15] op_sel_hi:[1,0,1]
	v_pk_mul_f32 v[0:1], v[82:83], v[0:1] op_sel:[1,0] op_sel_hi:[0,0]
	v_mov_b32_e32 v2, v3
	v_mul_lo_u32 v8, v84, s0
	s_mov_b32 s0, 0x2400000
	v_pk_fma_f32 v[48:49], v[26:27], v[82:83], v[50:51] op_sel_hi:[0,1,1] neg_lo:[0,0,1] neg_hi:[0,0,1]
	v_pk_fma_f32 v[50:51], v[26:27], v[82:83], v[50:51] op_sel_hi:[0,1,1]
	v_pk_fma_f32 v[26:27], v[24:25], v[82:83], v[30:31] op_sel_hi:[0,1,1] neg_lo:[0,0,1] neg_hi:[0,0,1]
	v_pk_fma_f32 v[30:31], v[24:25], v[82:83], v[30:31] op_sel_hi:[0,1,1]
	v_pk_fma_f32 v[56:57], v[18:19], v[82:83], v[58:59] op_sel_hi:[0,1,1] neg_lo:[0,0,1] neg_hi:[0,0,1]
	v_pk_fma_f32 v[58:59], v[18:19], v[82:83], v[58:59] op_sel_hi:[0,1,1]
	v_pk_fma_f32 v[18:19], v[16:17], v[82:83], v[22:23] op_sel_hi:[0,1,1] neg_lo:[0,0,1] neg_hi:[0,0,1]
	v_pk_fma_f32 v[22:23], v[16:17], v[82:83], v[22:23] op_sel_hi:[0,1,1]
	v_pk_fma_f32 v[80:81], v[82:83], v[2:3], v[0:1] op_sel_hi:[1,0,1] neg_lo:[0,0,1] neg_hi:[0,0,1]
	v_pk_fma_f32 v[82:83], v[82:83], v[2:3], v[0:1] op_sel_hi:[1,0,1]
	v_mul_lo_u32 v0, v86, s0
	v_readlane_b32 s0, v253, 27
	v_mov_b32_e32 v1, v96
	v_readlane_b32 s1, v253, 28
	v_cmp_eq_u32_e32 vcc, 0, v86
	v_mov_b64_e32 v[2:3], s[96:97]
	v_lshl_add_u64 v[84:85], s[0:1], 0, v[0:1]
	v_xad_u32 v0, v109, -1, v90
	v_cndmask_b32_e32 v0, v0, v109, vcc
	v_lshl_add_u64 v[0:1], v[32:33], 0, v[0:1]
	v_mad_u64_u32 v[2:3], s[0:1], v0, s43, v[2:3]
	v_mov_b32_e32 v0, v3
	v_mad_u64_u32 v[0:1], s[0:1], v1, s43, v[0:1]
	v_mov_b32_e32 v3, v0
	v_lshl_add_u64 v[4:5], v[2:3], 0, v[126:127]
	global_load_dwordx4 v[0:3], v[4:5], off offset:3088
	s_nop 0
	global_load_dwordx4 v[4:7], v[4:5], off offset:3072
	s_movk_i32 s0, 0x210
	v_mad_u32_u24 v22, v109, s0, v8
	v_lshrrev_b32_e32 v24, 2, v146
	v_lshl_or_b32 v22, v87, 2, v22
	v_and_b32_e32 v24, 12, v24
	v_lshl_add_u64 v[84:85], v[84:85], 0, v[126:127]
	v_lshlrev_b32_e32 v86, 1, v109
	v_mov_b32_e32 v87, v96
	v_lshl_add_u32 v30, v41, 6, v8
	v_mul_i32_i24_e32 v44, 0xffffffc4, v41
	v_sub_u32_e32 v39, v90, v109
	v_mov_b32_e32 v29, v45
	v_mov_b32_e32 v47, v25
	v_mov_b32_e32 v49, v51
	v_mov_b32_e32 v27, v31
	v_mov_b32_e32 v21, v53
	v_mov_b32_e32 v55, v17
	v_mov_b32_e32 v57, v59
	v_mov_b32_e32 v19, v23
	v_mov_b32_e32 v13, v61
	v_mov_b32_e32 v63, v9
	v_mov_b32_e32 v65, v67
	v_mov_b32_e32 v11, v15
	v_mov_b32_e32 v69, v71
	v_mov_b32_e32 v73, v75
	v_mov_b32_e32 v77, v79
	v_mov_b32_e32 v81, v83
	v_lshrrev_b32_e32 v14, 4, v90
	v_lshl_or_b32 v16, v41, 2, v8
	v_lshl_add_u64 v[84:85], v[84:85], 0, v[86:87]
	v_mov_b32_e32 v41, v40
	v_lshl_add_u64 v[86:87], s[96:97], 0, v[126:127]
	v_xad_u32 v35, v24, -1, v90
	v_or_b32_e32 v37, 16, v109
	v_subrev_u32_e32 v39, 17, v39
	v_add_u32_e32 v44, v30, v44
	v_xor_b32_e32 v50, 0x80000000, v110
	v_xor_b32_e32 v52, 0x80000000, v111
	v_xor_b32_e32 v58, 0x80000000, v112
	v_xor_b32_e32 v60, 0x80000000, v113
	v_xor_b32_e32 v66, 0x80000000, v114
	v_xor_b32_e32 v70, 0x80000000, v115
	v_xor_b32_e32 v74, 0x80000000, v116
	v_xor_b32_e32 v78, 0x80000000, v117
	v_xor_b32_e32 v82, 0x80000000, v118
	s_waitcnt vmcnt(7)
	v_xor_b32_e32 v109, 0x80000000, v120
	s_waitcnt vmcnt(6)
	v_xor_b32_e32 v110, 0x80000000, v121
	s_waitcnt vmcnt(5)
	v_xor_b32_e32 v111, 0x80000000, v122
	s_waitcnt vmcnt(4)
	v_xor_b32_e32 v112, 0x80000000, v123
	s_waitcnt vmcnt(3)
	v_xor_b32_e32 v113, 0x80000000, v124
	s_waitcnt vmcnt(2)
	v_xor_b32_e32 v114, 0x80000000, v125
	v_mov_b32_e32 v176, v28
	v_mov_b32_e32 v177, v25
	v_mov_b32_e32 v178, v46
	v_mov_b32_e32 v179, v45
	v_mov_b32_e32 v180, v48
	v_mov_b32_e32 v181, v51
	v_mov_b32_e32 v182, v26
	v_mov_b32_e32 v183, v31
	v_mov_b32_e32 v184, v20
	v_mov_b32_e32 v185, v17
	v_mov_b32_e32 v186, v54
	v_mov_b32_e32 v187, v53
	v_mov_b32_e32 v188, v56
	v_mov_b32_e32 v189, v59
	v_mov_b32_e32 v190, v18
	v_mov_b32_e32 v191, v23
	v_mov_b32_e32 v192, v12
	v_mov_b32_e32 v193, v9
	v_mov_b32_e32 v194, v62
	v_mov_b32_e32 v195, v61
	v_mov_b32_e32 v196, v64
	v_mov_b32_e32 v197, v67
	v_mov_b32_e32 v198, v10
	v_mov_b32_e32 v199, v15
	v_mov_b32_e32 v200, v68
	v_mov_b32_e32 v201, v75
	v_mov_b32_e32 v202, v72
	v_mov_b32_e32 v203, v71
	v_mov_b32_e32 v160, v76
	v_mov_b32_e32 v161, v79
	v_mov_b32_e32 v162, v80
	v_mov_b32_e32 v163, v83
	v_mov_b32_e32 v248, v40
	v_mov_b32_e32 v249, v42
	s_mov_b32 s15, 0
	s_branch .LBB0_744
.LBB0_743:
	s_or_b64 exec, exec, s[10:11]
	ds_read_b128 v[116:119], v8
	ds_read_b128 v[120:123], v8 offset:16
	ds_read_b128 v[124:127], v8 offset:32
	ds_read_b128 v[128:131], v8 offset:48
	s_movk_i32 s0, 0x7fff
	v_add_u32_e32 v39, -16, v39
	ds_read_b128 v[230:233], v8 offset:64
	ds_read_b128 v[234:237], v8 offset:80
	ds_read_b128 v[238:241], v8 offset:96
	ds_read_b128 v[242:245], v8 offset:112
	s_waitcnt lgkmcnt(4)
	v_pk_mul_f32 v[164:165], v[176:177], v[116:117] op_sel:[0,1] op_sel_hi:[1,1]
	v_pk_mul_f32 v[166:167], v[184:185], v[120:121] op_sel:[0,1] op_sel_hi:[1,1]
	v_pk_mul_f32 v[168:169], v[192:193], v[124:125] op_sel:[0,1] op_sel_hi:[1,1]
	v_pk_mul_f32 v[170:171], v[200:201], v[128:129] op_sel:[0,1] op_sel_hi:[1,1]
	v_pk_fma_f32 v[164:165], v[178:179], v[116:117], v[164:165] op_sel_hi:[1,0,1]
	v_pk_fma_f32 v[166:167], v[186:187], v[120:121], v[166:167] op_sel_hi:[1,0,1]
	v_pk_fma_f32 v[168:169], v[194:195], v[124:125], v[168:169] op_sel_hi:[1,0,1]
	v_pk_fma_f32 v[170:171], v[202:203], v[128:129], v[170:171] op_sel_hi:[1,0,1]
	v_pk_fma_f32 v[164:165], v[180:181], v[118:119], v[164:165] op_sel_hi:[1,0,1]
	v_pk_fma_f32 v[166:167], v[188:189], v[122:123], v[166:167] op_sel_hi:[1,0,1]
	v_pk_fma_f32 v[168:169], v[196:197], v[126:127], v[168:169] op_sel_hi:[1,0,1]
	v_pk_fma_f32 v[170:171], v[160:161], v[130:131], v[170:171] op_sel_hi:[1,0,1]
	v_pk_fma_f32 v[164:165], v[182:183], v[118:119], v[164:165] op_sel:[0,1,0] op_sel_hi:[1,1,1]
	v_pk_fma_f32 v[166:167], v[190:191], v[122:123], v[166:167] op_sel:[0,1,0] op_sel_hi:[1,1,1]
	v_pk_fma_f32 v[168:169], v[198:199], v[126:127], v[168:169] op_sel:[0,1,0] op_sel_hi:[1,1,1]
	v_pk_fma_f32 v[170:171], v[162:163], v[130:131], v[170:171] op_sel:[0,1,0] op_sel_hi:[1,1,1]
	v_pk_mul_f32 v[246:247], v[248:249], v[88:89] op_sel:[1,1] op_sel_hi:[0,1]
	v_pk_add_f32 v[164:165], v[164:165], v[166:167]
	v_pk_fma_f32 v[246:247], v[248:249], v[88:89], v[246:247] op_sel_hi:[1,0,1] neg_lo:[0,0,1]
	v_pk_add_f32 v[164:165], v[164:165], v[168:169]
	s_nop 0
	v_pk_add_f32 v[172:173], v[164:165], v[170:171]
	s_nop 0
	v_pk_add_f32 v[88:89], v[246:247], v[172:173]
	ds_write_b32 v16, v88 offset:1024
	ds_write_b32 v44, v89 offset:1280
	ds_read_b128 v[116:119], v8 offset:128
	ds_read_b128 v[120:123], v8 offset:144
	ds_read_b128 v[124:127], v8 offset:160
	ds_read_b128 v[128:131], v8 offset:176
	s_waitcnt lgkmcnt(6)
	v_pk_mul_f32 v[164:165], v[176:177], v[230:231] op_sel:[0,1] op_sel_hi:[1,1]
	v_pk_mul_f32 v[166:167], v[184:185], v[234:235] op_sel:[0,1] op_sel_hi:[1,1]
	v_pk_mul_f32 v[168:169], v[192:193], v[238:239] op_sel:[0,1] op_sel_hi:[1,1]
	v_pk_mul_f32 v[170:171], v[200:201], v[242:243] op_sel:[0,1] op_sel_hi:[1,1]
	v_pk_fma_f32 v[164:165], v[178:179], v[230:231], v[164:165] op_sel_hi:[1,0,1]
	v_pk_fma_f32 v[166:167], v[186:187], v[234:235], v[166:167] op_sel_hi:[1,0,1]
	v_pk_fma_f32 v[168:169], v[194:195], v[238:239], v[168:169] op_sel_hi:[1,0,1]
	v_pk_fma_f32 v[170:171], v[202:203], v[242:243], v[170:171] op_sel_hi:[1,0,1]
	v_pk_fma_f32 v[164:165], v[180:181], v[232:233], v[164:165] op_sel_hi:[1,0,1]
	v_pk_fma_f32 v[166:167], v[188:189], v[236:237], v[166:167] op_sel_hi:[1,0,1]
	v_pk_fma_f32 v[168:169], v[196:197], v[240:241], v[168:169] op_sel_hi:[1,0,1]
	v_pk_fma_f32 v[170:171], v[160:161], v[244:245], v[170:171] op_sel_hi:[1,0,1]
	v_pk_fma_f32 v[164:165], v[182:183], v[232:233], v[164:165] op_sel:[0,1,0] op_sel_hi:[1,1,1]
	v_pk_fma_f32 v[166:167], v[190:191], v[236:237], v[166:167] op_sel:[0,1,0] op_sel_hi:[1,1,1]
	v_pk_fma_f32 v[168:169], v[198:199], v[240:241], v[168:169] op_sel:[0,1,0] op_sel_hi:[1,1,1]
	v_pk_fma_f32 v[170:171], v[162:163], v[244:245], v[170:171] op_sel:[0,1,0] op_sel_hi:[1,1,1]
	v_pk_mul_f32 v[246:247], v[248:249], v[88:89] op_sel:[1,1] op_sel_hi:[0,1]
	v_pk_add_f32 v[164:165], v[164:165], v[166:167]
	v_pk_fma_f32 v[246:247], v[248:249], v[88:89], v[246:247] op_sel_hi:[1,0,1] neg_lo:[0,0,1]
	v_pk_add_f32 v[164:165], v[164:165], v[168:169]
	s_nop 0
	v_pk_add_f32 v[172:173], v[164:165], v[170:171]
	s_nop 0
	v_pk_add_f32 v[88:89], v[246:247], v[172:173]
	ds_write_b32 v16, v88 offset:1552
	ds_write_b32 v44, v89 offset:1808
	ds_read_b128 v[230:233], v8 offset:192
	ds_read_b128 v[234:237], v8 offset:208
	ds_read_b128 v[238:241], v8 offset:224
	ds_read_b128 v[242:245], v8 offset:240
	s_waitcnt lgkmcnt(6)
	v_pk_mul_f32 v[164:165], v[176:177], v[116:117] op_sel:[0,1] op_sel_hi:[1,1]
	v_pk_mul_f32 v[166:167], v[184:185], v[120:121] op_sel:[0,1] op_sel_hi:[1,1]
	v_pk_mul_f32 v[168:169], v[192:193], v[124:125] op_sel:[0,1] op_sel_hi:[1,1]
	v_pk_mul_f32 v[170:171], v[200:201], v[128:129] op_sel:[0,1] op_sel_hi:[1,1]
	v_pk_fma_f32 v[164:165], v[178:179], v[116:117], v[164:165] op_sel_hi:[1,0,1]
	v_pk_fma_f32 v[166:167], v[186:187], v[120:121], v[166:167] op_sel_hi:[1,0,1]
	v_pk_fma_f32 v[168:169], v[194:195], v[124:125], v[168:169] op_sel_hi:[1,0,1]
	v_pk_fma_f32 v[170:171], v[202:203], v[128:129], v[170:171] op_sel_hi:[1,0,1]
	v_pk_fma_f32 v[164:165], v[180:181], v[118:119], v[164:165] op_sel_hi:[1,0,1]
	v_pk_fma_f32 v[166:167], v[188:189], v[122:123], v[166:167] op_sel_hi:[1,0,1]
	v_pk_fma_f32 v[168:169], v[196:197], v[126:127], v[168:169] op_sel_hi:[1,0,1]
	v_pk_fma_f32 v[170:171], v[160:161], v[130:131], v[170:171] op_sel_hi:[1,0,1]
	v_pk_fma_f32 v[164:165], v[182:183], v[118:119], v[164:165] op_sel:[0,1,0] op_sel_hi:[1,1,1]
	v_pk_fma_f32 v[166:167], v[190:191], v[122:123], v[166:167] op_sel:[0,1,0] op_sel_hi:[1,1,1]
	v_pk_fma_f32 v[168:169], v[198:199], v[126:127], v[168:169] op_sel:[0,1,0] op_sel_hi:[1,1,1]
	v_pk_fma_f32 v[170:171], v[162:163], v[130:131], v[170:171] op_sel:[0,1,0] op_sel_hi:[1,1,1]
	v_pk_mul_f32 v[246:247], v[248:249], v[88:89] op_sel:[1,1] op_sel_hi:[0,1]
	v_pk_add_f32 v[164:165], v[164:165], v[166:167]
	v_pk_fma_f32 v[246:247], v[248:249], v[88:89], v[246:247] op_sel_hi:[1,0,1] neg_lo:[0,0,1]
	v_pk_add_f32 v[164:165], v[164:165], v[168:169]
	s_nop 0
	v_pk_add_f32 v[172:173], v[164:165], v[170:171]
	s_nop 0
	v_pk_add_f32 v[88:89], v[246:247], v[172:173]
	ds_write_b32 v16, v88 offset:2080
	ds_write_b32 v44, v89 offset:2336
	ds_read_b128 v[116:119], v8 offset:256
	ds_read_b128 v[120:123], v8 offset:272
	ds_read_b128 v[124:127], v8 offset:288
	ds_read_b128 v[128:131], v8 offset:304
	s_waitcnt lgkmcnt(6)
	v_pk_mul_f32 v[164:165], v[176:177], v[230:231] op_sel:[0,1] op_sel_hi:[1,1]
	v_pk_mul_f32 v[166:167], v[184:185], v[234:235] op_sel:[0,1] op_sel_hi:[1,1]
	v_pk_mul_f32 v[168:169], v[192:193], v[238:239] op_sel:[0,1] op_sel_hi:[1,1]
	v_pk_mul_f32 v[170:171], v[200:201], v[242:243] op_sel:[0,1] op_sel_hi:[1,1]
	v_pk_fma_f32 v[164:165], v[178:179], v[230:231], v[164:165] op_sel_hi:[1,0,1]
	v_pk_fma_f32 v[166:167], v[186:187], v[234:235], v[166:167] op_sel_hi:[1,0,1]
	v_pk_fma_f32 v[168:169], v[194:195], v[238:239], v[168:169] op_sel_hi:[1,0,1]
	v_pk_fma_f32 v[170:171], v[202:203], v[242:243], v[170:171] op_sel_hi:[1,0,1]
	v_pk_fma_f32 v[164:165], v[180:181], v[232:233], v[164:165] op_sel_hi:[1,0,1]
	v_pk_fma_f32 v[166:167], v[188:189], v[236:237], v[166:167] op_sel_hi:[1,0,1]
	v_pk_fma_f32 v[168:169], v[196:197], v[240:241], v[168:169] op_sel_hi:[1,0,1]
	v_pk_fma_f32 v[170:171], v[160:161], v[244:245], v[170:171] op_sel_hi:[1,0,1]
	v_pk_fma_f32 v[164:165], v[182:183], v[232:233], v[164:165] op_sel:[0,1,0] op_sel_hi:[1,1,1]
	v_pk_fma_f32 v[166:167], v[190:191], v[236:237], v[166:167] op_sel:[0,1,0] op_sel_hi:[1,1,1]
	v_pk_fma_f32 v[168:169], v[198:199], v[240:241], v[168:169] op_sel:[0,1,0] op_sel_hi:[1,1,1]
	v_pk_fma_f32 v[170:171], v[162:163], v[244:245], v[170:171] op_sel:[0,1,0] op_sel_hi:[1,1,1]
	v_pk_mul_f32 v[246:247], v[248:249], v[88:89] op_sel:[1,1] op_sel_hi:[0,1]
	v_pk_add_f32 v[164:165], v[164:165], v[166:167]
	v_pk_fma_f32 v[246:247], v[248:249], v[88:89], v[246:247] op_sel_hi:[1,0,1] neg_lo:[0,0,1]
	v_pk_add_f32 v[164:165], v[164:165], v[168:169]
	s_nop 0
	v_pk_add_f32 v[172:173], v[164:165], v[170:171]
	s_nop 0
	v_pk_add_f32 v[88:89], v[246:247], v[172:173]
	ds_write_b32 v16, v88 offset:2608
	ds_write_b32 v44, v89 offset:2864
	ds_read_b128 v[230:233], v8 offset:320
	ds_read_b128 v[234:237], v8 offset:336
	ds_read_b128 v[238:241], v8 offset:352
	ds_read_b128 v[242:245], v8 offset:368
	s_waitcnt lgkmcnt(6)
	v_pk_mul_f32 v[164:165], v[176:177], v[116:117] op_sel:[0,1] op_sel_hi:[1,1]
	v_pk_mul_f32 v[166:167], v[184:185], v[120:121] op_sel:[0,1] op_sel_hi:[1,1]
	v_pk_mul_f32 v[168:169], v[192:193], v[124:125] op_sel:[0,1] op_sel_hi:[1,1]
	v_pk_mul_f32 v[170:171], v[200:201], v[128:129] op_sel:[0,1] op_sel_hi:[1,1]
	v_pk_fma_f32 v[164:165], v[178:179], v[116:117], v[164:165] op_sel_hi:[1,0,1]
	v_pk_fma_f32 v[166:167], v[186:187], v[120:121], v[166:167] op_sel_hi:[1,0,1]
	v_pk_fma_f32 v[168:169], v[194:195], v[124:125], v[168:169] op_sel_hi:[1,0,1]
	v_pk_fma_f32 v[170:171], v[202:203], v[128:129], v[170:171] op_sel_hi:[1,0,1]
	v_pk_fma_f32 v[164:165], v[180:181], v[118:119], v[164:165] op_sel_hi:[1,0,1]
	v_pk_fma_f32 v[166:167], v[188:189], v[122:123], v[166:167] op_sel_hi:[1,0,1]
	v_pk_fma_f32 v[168:169], v[196:197], v[126:127], v[168:169] op_sel_hi:[1,0,1]
	v_pk_fma_f32 v[170:171], v[160:161], v[130:131], v[170:171] op_sel_hi:[1,0,1]
	v_pk_fma_f32 v[164:165], v[182:183], v[118:119], v[164:165] op_sel:[0,1,0] op_sel_hi:[1,1,1]
	v_pk_fma_f32 v[166:167], v[190:191], v[122:123], v[166:167] op_sel:[0,1,0] op_sel_hi:[1,1,1]
	v_pk_fma_f32 v[168:169], v[198:199], v[126:127], v[168:169] op_sel:[0,1,0] op_sel_hi:[1,1,1]
	v_pk_fma_f32 v[170:171], v[162:163], v[130:131], v[170:171] op_sel:[0,1,0] op_sel_hi:[1,1,1]
	v_pk_mul_f32 v[246:247], v[248:249], v[88:89] op_sel:[1,1] op_sel_hi:[0,1]
	v_pk_add_f32 v[164:165], v[164:165], v[166:167]
	v_pk_fma_f32 v[246:247], v[248:249], v[88:89], v[246:247] op_sel_hi:[1,0,1] neg_lo:[0,0,1]
	v_pk_add_f32 v[164:165], v[164:165], v[168:169]
	s_nop 0
	v_pk_add_f32 v[172:173], v[164:165], v[170:171]
	s_nop 0
	v_pk_add_f32 v[88:89], v[246:247], v[172:173]
	ds_write_b32 v16, v88 offset:3136
	ds_write_b32 v44, v89 offset:3392
	ds_read_b128 v[116:119], v8 offset:384
	ds_read_b128 v[120:123], v8 offset:400
	ds_read_b128 v[124:127], v8 offset:416
	ds_read_b128 v[128:131], v8 offset:432
	s_waitcnt lgkmcnt(6)
	v_pk_mul_f32 v[164:165], v[176:177], v[230:231] op_sel:[0,1] op_sel_hi:[1,1]
	v_pk_mul_f32 v[166:167], v[184:185], v[234:235] op_sel:[0,1] op_sel_hi:[1,1]
	v_pk_mul_f32 v[168:169], v[192:193], v[238:239] op_sel:[0,1] op_sel_hi:[1,1]
	v_pk_mul_f32 v[170:171], v[200:201], v[242:243] op_sel:[0,1] op_sel_hi:[1,1]
	v_pk_fma_f32 v[164:165], v[178:179], v[230:231], v[164:165] op_sel_hi:[1,0,1]
	v_pk_fma_f32 v[166:167], v[186:187], v[234:235], v[166:167] op_sel_hi:[1,0,1]
	v_pk_fma_f32 v[168:169], v[194:195], v[238:239], v[168:169] op_sel_hi:[1,0,1]
	v_pk_fma_f32 v[170:171], v[202:203], v[242:243], v[170:171] op_sel_hi:[1,0,1]
	v_pk_fma_f32 v[164:165], v[180:181], v[232:233], v[164:165] op_sel_hi:[1,0,1]
	v_pk_fma_f32 v[166:167], v[188:189], v[236:237], v[166:167] op_sel_hi:[1,0,1]
	v_pk_fma_f32 v[168:169], v[196:197], v[240:241], v[168:169] op_sel_hi:[1,0,1]
	v_pk_fma_f32 v[170:171], v[160:161], v[244:245], v[170:171] op_sel_hi:[1,0,1]
	v_pk_fma_f32 v[164:165], v[182:183], v[232:233], v[164:165] op_sel:[0,1,0] op_sel_hi:[1,1,1]
	v_pk_fma_f32 v[166:167], v[190:191], v[236:237], v[166:167] op_sel:[0,1,0] op_sel_hi:[1,1,1]
	v_pk_fma_f32 v[168:169], v[198:199], v[240:241], v[168:169] op_sel:[0,1,0] op_sel_hi:[1,1,1]
	v_pk_fma_f32 v[170:171], v[162:163], v[244:245], v[170:171] op_sel:[0,1,0] op_sel_hi:[1,1,1]
	v_pk_mul_f32 v[246:247], v[248:249], v[88:89] op_sel:[1,1] op_sel_hi:[0,1]
	v_pk_add_f32 v[164:165], v[164:165], v[166:167]
	v_pk_fma_f32 v[246:247], v[248:249], v[88:89], v[246:247] op_sel_hi:[1,0,1] neg_lo:[0,0,1]
	v_pk_add_f32 v[164:165], v[164:165], v[168:169]
	s_nop 0
	v_pk_add_f32 v[172:173], v[164:165], v[170:171]
	s_nop 0
	v_pk_add_f32 v[88:89], v[246:247], v[172:173]
	ds_write_b32 v16, v88 offset:3664
	ds_write_b32 v44, v89 offset:3920
	ds_read_b128 v[230:233], v8 offset:448
	ds_read_b128 v[234:237], v8 offset:464
	ds_read_b128 v[238:241], v8 offset:480
	ds_read_b128 v[242:245], v8 offset:496
	s_waitcnt lgkmcnt(6)
	v_pk_mul_f32 v[164:165], v[176:177], v[116:117] op_sel:[0,1] op_sel_hi:[1,1]
	v_pk_mul_f32 v[166:167], v[184:185], v[120:121] op_sel:[0,1] op_sel_hi:[1,1]
	v_pk_mul_f32 v[168:169], v[192:193], v[124:125] op_sel:[0,1] op_sel_hi:[1,1]
	v_pk_mul_f32 v[170:171], v[200:201], v[128:129] op_sel:[0,1] op_sel_hi:[1,1]
	v_pk_fma_f32 v[164:165], v[178:179], v[116:117], v[164:165] op_sel_hi:[1,0,1]
	v_pk_fma_f32 v[166:167], v[186:187], v[120:121], v[166:167] op_sel_hi:[1,0,1]
	v_pk_fma_f32 v[168:169], v[194:195], v[124:125], v[168:169] op_sel_hi:[1,0,1]
	v_pk_fma_f32 v[170:171], v[202:203], v[128:129], v[170:171] op_sel_hi:[1,0,1]
	v_pk_fma_f32 v[164:165], v[180:181], v[118:119], v[164:165] op_sel_hi:[1,0,1]
	v_pk_fma_f32 v[166:167], v[188:189], v[122:123], v[166:167] op_sel_hi:[1,0,1]
	v_pk_fma_f32 v[168:169], v[196:197], v[126:127], v[168:169] op_sel_hi:[1,0,1]
	v_pk_fma_f32 v[170:171], v[160:161], v[130:131], v[170:171] op_sel_hi:[1,0,1]
	v_pk_fma_f32 v[164:165], v[182:183], v[118:119], v[164:165] op_sel:[0,1,0] op_sel_hi:[1,1,1]
	v_pk_fma_f32 v[166:167], v[190:191], v[122:123], v[166:167] op_sel:[0,1,0] op_sel_hi:[1,1,1]
	v_pk_fma_f32 v[168:169], v[198:199], v[126:127], v[168:169] op_sel:[0,1,0] op_sel_hi:[1,1,1]
	v_pk_fma_f32 v[170:171], v[162:163], v[130:131], v[170:171] op_sel:[0,1,0] op_sel_hi:[1,1,1]
	v_pk_mul_f32 v[246:247], v[248:249], v[88:89] op_sel:[1,1] op_sel_hi:[0,1]
	v_pk_add_f32 v[164:165], v[164:165], v[166:167]
	v_pk_fma_f32 v[246:247], v[248:249], v[88:89], v[246:247] op_sel_hi:[1,0,1] neg_lo:[0,0,1]
	v_pk_add_f32 v[164:165], v[164:165], v[168:169]
	s_nop 0
	v_pk_add_f32 v[172:173], v[164:165], v[170:171]
	s_nop 0
	v_pk_add_f32 v[88:89], v[246:247], v[172:173]
	ds_write_b32 v16, v88 offset:4192
	ds_write_b32 v44, v89 offset:4448
	ds_read_b128 v[116:119], v8 offset:512
	ds_read_b128 v[120:123], v8 offset:528
	ds_read_b128 v[124:127], v8 offset:544
	ds_read_b128 v[128:131], v8 offset:560
	s_waitcnt lgkmcnt(6)
	v_pk_mul_f32 v[164:165], v[176:177], v[230:231] op_sel:[0,1] op_sel_hi:[1,1]
	v_pk_mul_f32 v[166:167], v[184:185], v[234:235] op_sel:[0,1] op_sel_hi:[1,1]
	v_pk_mul_f32 v[168:169], v[192:193], v[238:239] op_sel:[0,1] op_sel_hi:[1,1]
	v_pk_mul_f32 v[170:171], v[200:201], v[242:243] op_sel:[0,1] op_sel_hi:[1,1]
	v_pk_fma_f32 v[164:165], v[178:179], v[230:231], v[164:165] op_sel_hi:[1,0,1]
	v_pk_fma_f32 v[166:167], v[186:187], v[234:235], v[166:167] op_sel_hi:[1,0,1]
	v_pk_fma_f32 v[168:169], v[194:195], v[238:239], v[168:169] op_sel_hi:[1,0,1]
	v_pk_fma_f32 v[170:171], v[202:203], v[242:243], v[170:171] op_sel_hi:[1,0,1]
	v_pk_fma_f32 v[164:165], v[180:181], v[232:233], v[164:165] op_sel_hi:[1,0,1]
	v_pk_fma_f32 v[166:167], v[188:189], v[236:237], v[166:167] op_sel_hi:[1,0,1]
	v_pk_fma_f32 v[168:169], v[196:197], v[240:241], v[168:169] op_sel_hi:[1,0,1]
	v_pk_fma_f32 v[170:171], v[160:161], v[244:245], v[170:171] op_sel_hi:[1,0,1]
	v_pk_fma_f32 v[164:165], v[182:183], v[232:233], v[164:165] op_sel:[0,1,0] op_sel_hi:[1,1,1]
	v_pk_fma_f32 v[166:167], v[190:191], v[236:237], v[166:167] op_sel:[0,1,0] op_sel_hi:[1,1,1]
	v_pk_fma_f32 v[168:169], v[198:199], v[240:241], v[168:169] op_sel:[0,1,0] op_sel_hi:[1,1,1]
	v_pk_fma_f32 v[170:171], v[162:163], v[244:245], v[170:171] op_sel:[0,1,0] op_sel_hi:[1,1,1]
	v_pk_mul_f32 v[246:247], v[248:249], v[88:89] op_sel:[1,1] op_sel_hi:[0,1]
	v_pk_add_f32 v[164:165], v[164:165], v[166:167]
	v_pk_fma_f32 v[246:247], v[248:249], v[88:89], v[246:247] op_sel_hi:[1,0,1] neg_lo:[0,0,1]
	v_pk_add_f32 v[164:165], v[164:165], v[168:169]
	s_nop 0
	v_pk_add_f32 v[172:173], v[164:165], v[170:171]
	s_nop 0
	v_pk_add_f32 v[88:89], v[246:247], v[172:173]
	ds_write_b32 v16, v88 offset:4720
	ds_write_b32 v44, v89 offset:4976
	ds_read_b128 v[230:233], v8 offset:576
	ds_read_b128 v[234:237], v8 offset:592
	ds_read_b128 v[238:241], v8 offset:608
	ds_read_b128 v[242:245], v8 offset:624
	s_waitcnt lgkmcnt(6)
	v_pk_mul_f32 v[164:165], v[176:177], v[116:117] op_sel:[0,1] op_sel_hi:[1,1]
	v_pk_mul_f32 v[166:167], v[184:185], v[120:121] op_sel:[0,1] op_sel_hi:[1,1]
	v_pk_mul_f32 v[168:169], v[192:193], v[124:125] op_sel:[0,1] op_sel_hi:[1,1]
	v_pk_mul_f32 v[170:171], v[200:201], v[128:129] op_sel:[0,1] op_sel_hi:[1,1]
	v_pk_fma_f32 v[164:165], v[178:179], v[116:117], v[164:165] op_sel_hi:[1,0,1]
	v_pk_fma_f32 v[166:167], v[186:187], v[120:121], v[166:167] op_sel_hi:[1,0,1]
	v_pk_fma_f32 v[168:169], v[194:195], v[124:125], v[168:169] op_sel_hi:[1,0,1]
	v_pk_fma_f32 v[170:171], v[202:203], v[128:129], v[170:171] op_sel_hi:[1,0,1]
	v_pk_fma_f32 v[164:165], v[180:181], v[118:119], v[164:165] op_sel_hi:[1,0,1]
	v_pk_fma_f32 v[166:167], v[188:189], v[122:123], v[166:167] op_sel_hi:[1,0,1]
	v_pk_fma_f32 v[168:169], v[196:197], v[126:127], v[168:169] op_sel_hi:[1,0,1]
	v_pk_fma_f32 v[170:171], v[160:161], v[130:131], v[170:171] op_sel_hi:[1,0,1]
	v_pk_fma_f32 v[164:165], v[182:183], v[118:119], v[164:165] op_sel:[0,1,0] op_sel_hi:[1,1,1]
	v_pk_fma_f32 v[166:167], v[190:191], v[122:123], v[166:167] op_sel:[0,1,0] op_sel_hi:[1,1,1]
	v_pk_fma_f32 v[168:169], v[198:199], v[126:127], v[168:169] op_sel:[0,1,0] op_sel_hi:[1,1,1]
	v_pk_fma_f32 v[170:171], v[162:163], v[130:131], v[170:171] op_sel:[0,1,0] op_sel_hi:[1,1,1]
	v_pk_mul_f32 v[246:247], v[248:249], v[88:89] op_sel:[1,1] op_sel_hi:[0,1]
	v_pk_add_f32 v[164:165], v[164:165], v[166:167]
	v_pk_fma_f32 v[246:247], v[248:249], v[88:89], v[246:247] op_sel_hi:[1,0,1] neg_lo:[0,0,1]
	v_pk_add_f32 v[164:165], v[164:165], v[168:169]
	s_nop 0
	v_pk_add_f32 v[172:173], v[164:165], v[170:171]
	s_nop 0
	v_pk_add_f32 v[88:89], v[246:247], v[172:173]
	ds_write_b32 v16, v88 offset:5248
	ds_write_b32 v44, v89 offset:5504
	ds_read_b128 v[116:119], v8 offset:640
	ds_read_b128 v[120:123], v8 offset:656
	ds_read_b128 v[124:127], v8 offset:672
	ds_read_b128 v[128:131], v8 offset:688
	s_waitcnt lgkmcnt(6)
	v_pk_mul_f32 v[164:165], v[176:177], v[230:231] op_sel:[0,1] op_sel_hi:[1,1]
	v_pk_mul_f32 v[166:167], v[184:185], v[234:235] op_sel:[0,1] op_sel_hi:[1,1]
	v_pk_mul_f32 v[168:169], v[192:193], v[238:239] op_sel:[0,1] op_sel_hi:[1,1]
	v_pk_mul_f32 v[170:171], v[200:201], v[242:243] op_sel:[0,1] op_sel_hi:[1,1]
	v_pk_fma_f32 v[164:165], v[178:179], v[230:231], v[164:165] op_sel_hi:[1,0,1]
	v_pk_fma_f32 v[166:167], v[186:187], v[234:235], v[166:167] op_sel_hi:[1,0,1]
	v_pk_fma_f32 v[168:169], v[194:195], v[238:239], v[168:169] op_sel_hi:[1,0,1]
	v_pk_fma_f32 v[170:171], v[202:203], v[242:243], v[170:171] op_sel_hi:[1,0,1]
	v_pk_fma_f32 v[164:165], v[180:181], v[232:233], v[164:165] op_sel_hi:[1,0,1]
	v_pk_fma_f32 v[166:167], v[188:189], v[236:237], v[166:167] op_sel_hi:[1,0,1]
	v_pk_fma_f32 v[168:169], v[196:197], v[240:241], v[168:169] op_sel_hi:[1,0,1]
	v_pk_fma_f32 v[170:171], v[160:161], v[244:245], v[170:171] op_sel_hi:[1,0,1]
	v_pk_fma_f32 v[164:165], v[182:183], v[232:233], v[164:165] op_sel:[0,1,0] op_sel_hi:[1,1,1]
	v_pk_fma_f32 v[166:167], v[190:191], v[236:237], v[166:167] op_sel:[0,1,0] op_sel_hi:[1,1,1]
	v_pk_fma_f32 v[168:169], v[198:199], v[240:241], v[168:169] op_sel:[0,1,0] op_sel_hi:[1,1,1]
	v_pk_fma_f32 v[170:171], v[162:163], v[244:245], v[170:171] op_sel:[0,1,0] op_sel_hi:[1,1,1]
	v_pk_mul_f32 v[246:247], v[248:249], v[88:89] op_sel:[1,1] op_sel_hi:[0,1]
	v_pk_add_f32 v[164:165], v[164:165], v[166:167]
	v_pk_fma_f32 v[246:247], v[248:249], v[88:89], v[246:247] op_sel_hi:[1,0,1] neg_lo:[0,0,1]
	v_pk_add_f32 v[164:165], v[164:165], v[168:169]
	s_nop 0
	v_pk_add_f32 v[172:173], v[164:165], v[170:171]
	s_nop 0
	v_pk_add_f32 v[88:89], v[246:247], v[172:173]
	ds_write_b32 v16, v88 offset:5776
	ds_write_b32 v44, v89 offset:6032
	ds_read_b128 v[230:233], v8 offset:704
	ds_read_b128 v[234:237], v8 offset:720
	ds_read_b128 v[238:241], v8 offset:736
	ds_read_b128 v[242:245], v8 offset:752
	s_waitcnt lgkmcnt(6)
	v_pk_mul_f32 v[164:165], v[176:177], v[116:117] op_sel:[0,1] op_sel_hi:[1,1]
	v_pk_mul_f32 v[166:167], v[184:185], v[120:121] op_sel:[0,1] op_sel_hi:[1,1]
	v_pk_mul_f32 v[168:169], v[192:193], v[124:125] op_sel:[0,1] op_sel_hi:[1,1]
	v_pk_mul_f32 v[170:171], v[200:201], v[128:129] op_sel:[0,1] op_sel_hi:[1,1]
	v_pk_fma_f32 v[164:165], v[178:179], v[116:117], v[164:165] op_sel_hi:[1,0,1]
	v_pk_fma_f32 v[166:167], v[186:187], v[120:121], v[166:167] op_sel_hi:[1,0,1]
	v_pk_fma_f32 v[168:169], v[194:195], v[124:125], v[168:169] op_sel_hi:[1,0,1]
	v_pk_fma_f32 v[170:171], v[202:203], v[128:129], v[170:171] op_sel_hi:[1,0,1]
	v_pk_fma_f32 v[164:165], v[180:181], v[118:119], v[164:165] op_sel_hi:[1,0,1]
	v_pk_fma_f32 v[166:167], v[188:189], v[122:123], v[166:167] op_sel_hi:[1,0,1]
	v_pk_fma_f32 v[168:169], v[196:197], v[126:127], v[168:169] op_sel_hi:[1,0,1]
	v_pk_fma_f32 v[170:171], v[160:161], v[130:131], v[170:171] op_sel_hi:[1,0,1]
	v_pk_fma_f32 v[164:165], v[182:183], v[118:119], v[164:165] op_sel:[0,1,0] op_sel_hi:[1,1,1]
	v_pk_fma_f32 v[166:167], v[190:191], v[122:123], v[166:167] op_sel:[0,1,0] op_sel_hi:[1,1,1]
	v_pk_fma_f32 v[168:169], v[198:199], v[126:127], v[168:169] op_sel:[0,1,0] op_sel_hi:[1,1,1]
	v_pk_fma_f32 v[170:171], v[162:163], v[130:131], v[170:171] op_sel:[0,1,0] op_sel_hi:[1,1,1]
	v_pk_mul_f32 v[246:247], v[248:249], v[88:89] op_sel:[1,1] op_sel_hi:[0,1]
	v_pk_add_f32 v[164:165], v[164:165], v[166:167]
	v_pk_fma_f32 v[246:247], v[248:249], v[88:89], v[246:247] op_sel_hi:[1,0,1] neg_lo:[0,0,1]
	v_pk_add_f32 v[164:165], v[164:165], v[168:169]
	s_nop 0
	v_pk_add_f32 v[172:173], v[164:165], v[170:171]
	s_nop 0
	v_pk_add_f32 v[88:89], v[246:247], v[172:173]
	ds_write_b32 v16, v88 offset:6304
	ds_write_b32 v44, v89 offset:6560
	ds_read_b128 v[116:119], v8 offset:768
	ds_read_b128 v[120:123], v8 offset:784
	ds_read_b128 v[124:127], v8 offset:800
	ds_read_b128 v[128:131], v8 offset:816
	s_waitcnt lgkmcnt(6)
	v_pk_mul_f32 v[164:165], v[176:177], v[230:231] op_sel:[0,1] op_sel_hi:[1,1]
	v_pk_mul_f32 v[166:167], v[184:185], v[234:235] op_sel:[0,1] op_sel_hi:[1,1]
	v_pk_mul_f32 v[168:169], v[192:193], v[238:239] op_sel:[0,1] op_sel_hi:[1,1]
	v_pk_mul_f32 v[170:171], v[200:201], v[242:243] op_sel:[0,1] op_sel_hi:[1,1]
	v_pk_fma_f32 v[164:165], v[178:179], v[230:231], v[164:165] op_sel_hi:[1,0,1]
	v_pk_fma_f32 v[166:167], v[186:187], v[234:235], v[166:167] op_sel_hi:[1,0,1]
	v_pk_fma_f32 v[168:169], v[194:195], v[238:239], v[168:169] op_sel_hi:[1,0,1]
	v_pk_fma_f32 v[170:171], v[202:203], v[242:243], v[170:171] op_sel_hi:[1,0,1]
	v_pk_fma_f32 v[164:165], v[180:181], v[232:233], v[164:165] op_sel_hi:[1,0,1]
	v_pk_fma_f32 v[166:167], v[188:189], v[236:237], v[166:167] op_sel_hi:[1,0,1]
	v_pk_fma_f32 v[168:169], v[196:197], v[240:241], v[168:169] op_sel_hi:[1,0,1]
	v_pk_fma_f32 v[170:171], v[160:161], v[244:245], v[170:171] op_sel_hi:[1,0,1]
	v_pk_fma_f32 v[164:165], v[182:183], v[232:233], v[164:165] op_sel:[0,1,0] op_sel_hi:[1,1,1]
	v_pk_fma_f32 v[166:167], v[190:191], v[236:237], v[166:167] op_sel:[0,1,0] op_sel_hi:[1,1,1]
	v_pk_fma_f32 v[168:169], v[198:199], v[240:241], v[168:169] op_sel:[0,1,0] op_sel_hi:[1,1,1]
	v_pk_fma_f32 v[170:171], v[162:163], v[244:245], v[170:171] op_sel:[0,1,0] op_sel_hi:[1,1,1]
	v_pk_mul_f32 v[246:247], v[248:249], v[88:89] op_sel:[1,1] op_sel_hi:[0,1]
	v_pk_add_f32 v[164:165], v[164:165], v[166:167]
	v_pk_fma_f32 v[246:247], v[248:249], v[88:89], v[246:247] op_sel_hi:[1,0,1] neg_lo:[0,0,1]
	v_pk_add_f32 v[164:165], v[164:165], v[168:169]
	s_nop 0
	v_pk_add_f32 v[172:173], v[164:165], v[170:171]
	s_nop 0
	v_pk_add_f32 v[88:89], v[246:247], v[172:173]
	ds_write_b32 v16, v88 offset:6832
	ds_write_b32 v44, v89 offset:7088
	ds_read_b128 v[230:233], v8 offset:832
	ds_read_b128 v[234:237], v8 offset:848
	ds_read_b128 v[238:241], v8 offset:864
	ds_read_b128 v[242:245], v8 offset:880
	s_waitcnt lgkmcnt(6)
	v_pk_mul_f32 v[164:165], v[176:177], v[116:117] op_sel:[0,1] op_sel_hi:[1,1]
	v_pk_mul_f32 v[166:167], v[184:185], v[120:121] op_sel:[0,1] op_sel_hi:[1,1]
	v_pk_mul_f32 v[168:169], v[192:193], v[124:125] op_sel:[0,1] op_sel_hi:[1,1]
	v_pk_mul_f32 v[170:171], v[200:201], v[128:129] op_sel:[0,1] op_sel_hi:[1,1]
	v_pk_fma_f32 v[164:165], v[178:179], v[116:117], v[164:165] op_sel_hi:[1,0,1]
	v_pk_fma_f32 v[166:167], v[186:187], v[120:121], v[166:167] op_sel_hi:[1,0,1]
	v_pk_fma_f32 v[168:169], v[194:195], v[124:125], v[168:169] op_sel_hi:[1,0,1]
	v_pk_fma_f32 v[170:171], v[202:203], v[128:129], v[170:171] op_sel_hi:[1,0,1]
	v_pk_fma_f32 v[164:165], v[180:181], v[118:119], v[164:165] op_sel_hi:[1,0,1]
	v_pk_fma_f32 v[166:167], v[188:189], v[122:123], v[166:167] op_sel_hi:[1,0,1]
	v_pk_fma_f32 v[168:169], v[196:197], v[126:127], v[168:169] op_sel_hi:[1,0,1]
	v_pk_fma_f32 v[170:171], v[160:161], v[130:131], v[170:171] op_sel_hi:[1,0,1]
	v_pk_fma_f32 v[164:165], v[182:183], v[118:119], v[164:165] op_sel:[0,1,0] op_sel_hi:[1,1,1]
	v_pk_fma_f32 v[166:167], v[190:191], v[122:123], v[166:167] op_sel:[0,1,0] op_sel_hi:[1,1,1]
	v_pk_fma_f32 v[168:169], v[198:199], v[126:127], v[168:169] op_sel:[0,1,0] op_sel_hi:[1,1,1]
	v_pk_fma_f32 v[170:171], v[162:163], v[130:131], v[170:171] op_sel:[0,1,0] op_sel_hi:[1,1,1]
	v_pk_mul_f32 v[246:247], v[248:249], v[88:89] op_sel:[1,1] op_sel_hi:[0,1]
	v_pk_add_f32 v[164:165], v[164:165], v[166:167]
	v_pk_fma_f32 v[246:247], v[248:249], v[88:89], v[246:247] op_sel_hi:[1,0,1] neg_lo:[0,0,1]
	v_pk_add_f32 v[164:165], v[164:165], v[168:169]
	s_nop 0
	v_pk_add_f32 v[172:173], v[164:165], v[170:171]
	s_nop 0
	v_pk_add_f32 v[88:89], v[246:247], v[172:173]
	ds_write_b32 v16, v88 offset:7360
	ds_write_b32 v44, v89 offset:7616
	ds_read_b128 v[116:119], v8 offset:896
	ds_read_b128 v[120:123], v8 offset:912
	ds_read_b128 v[124:127], v8 offset:928
	ds_read_b128 v[128:131], v8 offset:944
	s_waitcnt lgkmcnt(6)
	v_pk_mul_f32 v[164:165], v[176:177], v[230:231] op_sel:[0,1] op_sel_hi:[1,1]
	v_pk_mul_f32 v[166:167], v[184:185], v[234:235] op_sel:[0,1] op_sel_hi:[1,1]
	v_pk_mul_f32 v[168:169], v[192:193], v[238:239] op_sel:[0,1] op_sel_hi:[1,1]
	v_pk_mul_f32 v[170:171], v[200:201], v[242:243] op_sel:[0,1] op_sel_hi:[1,1]
	v_pk_fma_f32 v[164:165], v[178:179], v[230:231], v[164:165] op_sel_hi:[1,0,1]
	v_pk_fma_f32 v[166:167], v[186:187], v[234:235], v[166:167] op_sel_hi:[1,0,1]
	v_pk_fma_f32 v[168:169], v[194:195], v[238:239], v[168:169] op_sel_hi:[1,0,1]
	v_pk_fma_f32 v[170:171], v[202:203], v[242:243], v[170:171] op_sel_hi:[1,0,1]
	v_pk_fma_f32 v[164:165], v[180:181], v[232:233], v[164:165] op_sel_hi:[1,0,1]
	v_pk_fma_f32 v[166:167], v[188:189], v[236:237], v[166:167] op_sel_hi:[1,0,1]
	v_pk_fma_f32 v[168:169], v[196:197], v[240:241], v[168:169] op_sel_hi:[1,0,1]
	v_pk_fma_f32 v[170:171], v[160:161], v[244:245], v[170:171] op_sel_hi:[1,0,1]
	v_pk_fma_f32 v[164:165], v[182:183], v[232:233], v[164:165] op_sel:[0,1,0] op_sel_hi:[1,1,1]
	v_pk_fma_f32 v[166:167], v[190:191], v[236:237], v[166:167] op_sel:[0,1,0] op_sel_hi:[1,1,1]
	v_pk_fma_f32 v[168:169], v[198:199], v[240:241], v[168:169] op_sel:[0,1,0] op_sel_hi:[1,1,1]
	v_pk_fma_f32 v[170:171], v[162:163], v[244:245], v[170:171] op_sel:[0,1,0] op_sel_hi:[1,1,1]
	v_pk_mul_f32 v[246:247], v[248:249], v[88:89] op_sel:[1,1] op_sel_hi:[0,1]
	v_pk_add_f32 v[164:165], v[164:165], v[166:167]
	v_pk_fma_f32 v[246:247], v[248:249], v[88:89], v[246:247] op_sel_hi:[1,0,1] neg_lo:[0,0,1]
	v_pk_add_f32 v[164:165], v[164:165], v[168:169]
	s_nop 0
	v_pk_add_f32 v[172:173], v[164:165], v[170:171]
	s_nop 0
	v_pk_add_f32 v[88:89], v[246:247], v[172:173]
	ds_write_b32 v16, v88 offset:7888
	ds_write_b32 v44, v89 offset:8144
	ds_read_b128 v[230:233], v8 offset:960
	ds_read_b128 v[234:237], v8 offset:976
	ds_read_b128 v[238:241], v8 offset:992
	ds_read_b128 v[242:245], v8 offset:1008
	s_waitcnt lgkmcnt(6)
	v_pk_mul_f32 v[164:165], v[176:177], v[116:117] op_sel:[0,1] op_sel_hi:[1,1]
	v_pk_mul_f32 v[166:167], v[184:185], v[120:121] op_sel:[0,1] op_sel_hi:[1,1]
	v_pk_mul_f32 v[168:169], v[192:193], v[124:125] op_sel:[0,1] op_sel_hi:[1,1]
	v_pk_mul_f32 v[170:171], v[200:201], v[128:129] op_sel:[0,1] op_sel_hi:[1,1]
	v_pk_fma_f32 v[164:165], v[178:179], v[116:117], v[164:165] op_sel_hi:[1,0,1]
	v_pk_fma_f32 v[166:167], v[186:187], v[120:121], v[166:167] op_sel_hi:[1,0,1]
	v_pk_fma_f32 v[168:169], v[194:195], v[124:125], v[168:169] op_sel_hi:[1,0,1]
	v_pk_fma_f32 v[170:171], v[202:203], v[128:129], v[170:171] op_sel_hi:[1,0,1]
	v_pk_fma_f32 v[164:165], v[180:181], v[118:119], v[164:165] op_sel_hi:[1,0,1]
	v_pk_fma_f32 v[166:167], v[188:189], v[122:123], v[166:167] op_sel_hi:[1,0,1]
	v_pk_fma_f32 v[168:169], v[196:197], v[126:127], v[168:169] op_sel_hi:[1,0,1]
	v_pk_fma_f32 v[170:171], v[160:161], v[130:131], v[170:171] op_sel_hi:[1,0,1]
	v_pk_fma_f32 v[164:165], v[182:183], v[118:119], v[164:165] op_sel:[0,1,0] op_sel_hi:[1,1,1]
	v_pk_fma_f32 v[166:167], v[190:191], v[122:123], v[166:167] op_sel:[0,1,0] op_sel_hi:[1,1,1]
	v_pk_fma_f32 v[168:169], v[198:199], v[126:127], v[168:169] op_sel:[0,1,0] op_sel_hi:[1,1,1]
	v_pk_fma_f32 v[170:171], v[162:163], v[130:131], v[170:171] op_sel:[0,1,0] op_sel_hi:[1,1,1]
	v_pk_mul_f32 v[246:247], v[248:249], v[88:89] op_sel:[1,1] op_sel_hi:[0,1]
	v_pk_add_f32 v[164:165], v[164:165], v[166:167]
	v_pk_fma_f32 v[246:247], v[248:249], v[88:89], v[246:247] op_sel_hi:[1,0,1] neg_lo:[0,0,1]
	v_pk_add_f32 v[164:165], v[164:165], v[168:169]
	s_nop 0
	v_pk_add_f32 v[172:173], v[164:165], v[170:171]
	s_nop 0
	v_pk_add_f32 v[88:89], v[246:247], v[172:173]
	ds_write_b32 v16, v88 offset:8416
	ds_write_b32 v44, v89 offset:8672
	s_waitcnt lgkmcnt(2)
	v_pk_mul_f32 v[164:165], v[176:177], v[230:231] op_sel:[0,1] op_sel_hi:[1,1]
	v_pk_mul_f32 v[166:167], v[184:185], v[234:235] op_sel:[0,1] op_sel_hi:[1,1]
	v_pk_mul_f32 v[168:169], v[192:193], v[238:239] op_sel:[0,1] op_sel_hi:[1,1]
	v_pk_mul_f32 v[170:171], v[200:201], v[242:243] op_sel:[0,1] op_sel_hi:[1,1]
	v_pk_fma_f32 v[164:165], v[178:179], v[230:231], v[164:165] op_sel_hi:[1,0,1]
	v_pk_fma_f32 v[166:167], v[186:187], v[234:235], v[166:167] op_sel_hi:[1,0,1]
	v_pk_fma_f32 v[168:169], v[194:195], v[238:239], v[168:169] op_sel_hi:[1,0,1]
	v_pk_fma_f32 v[170:171], v[202:203], v[242:243], v[170:171] op_sel_hi:[1,0,1]
	v_pk_fma_f32 v[164:165], v[180:181], v[232:233], v[164:165] op_sel_hi:[1,0,1]
	v_pk_fma_f32 v[166:167], v[188:189], v[236:237], v[166:167] op_sel_hi:[1,0,1]
	v_pk_fma_f32 v[168:169], v[196:197], v[240:241], v[168:169] op_sel_hi:[1,0,1]
	v_pk_fma_f32 v[170:171], v[160:161], v[244:245], v[170:171] op_sel_hi:[1,0,1]
	v_pk_fma_f32 v[164:165], v[182:183], v[232:233], v[164:165] op_sel:[0,1,0] op_sel_hi:[1,1,1]
	v_pk_fma_f32 v[166:167], v[190:191], v[236:237], v[166:167] op_sel:[0,1,0] op_sel_hi:[1,1,1]
	v_pk_fma_f32 v[168:169], v[198:199], v[240:241], v[168:169] op_sel:[0,1,0] op_sel_hi:[1,1,1]
	v_pk_fma_f32 v[170:171], v[162:163], v[244:245], v[170:171] op_sel:[0,1,0] op_sel_hi:[1,1,1]
	v_pk_mul_f32 v[246:247], v[248:249], v[88:89] op_sel:[1,1] op_sel_hi:[0,1]
	v_pk_add_f32 v[164:165], v[164:165], v[166:167]
	v_pk_fma_f32 v[246:247], v[248:249], v[88:89], v[246:247] op_sel_hi:[1,0,1] neg_lo:[0,0,1]
	v_pk_add_f32 v[164:165], v[164:165], v[168:169]
	s_nop 0
	v_pk_add_f32 v[172:173], v[164:165], v[170:171]
	s_nop 0
	v_pk_add_f32 v[88:89], v[246:247], v[172:173]
	ds_write_b32 v16, v88 offset:8944
	ds_write_b32 v44, v89 offset:9200
	v_add_u32_e32 v115, 0x400, v22
	s_waitcnt lgkmcnt(0)
	s_barrier
	ds_read2_b32 v[120:121], v115 offset1:4
	s_waitcnt lgkmcnt(0)
	v_mfma_f32_16x16x4_f32 v[116:119], v120, v91, 0
	v_mfma_f32_16x16x4_f32 v[116:119], v121, v92, v[116:119]
	ds_read2_b32 v[120:121], v115 offset0:8 offset1:12
	s_waitcnt lgkmcnt(0)
	v_mfma_f32_16x16x4_f32 v[116:119], v120, v93, v[116:119]
	v_mfma_f32_16x16x4_f32 v[116:119], v121, v94, v[116:119]
	ds_read2_b32 v[120:121], v115 offset0:16 offset1:20
	s_waitcnt lgkmcnt(0)
	v_mfma_f32_16x16x4_f32 v[116:119], v120, v95, v[116:119]
	v_mfma_f32_16x16x4_f32 v[116:119], v121, v98, v[116:119]
	ds_read2_b32 v[120:121], v115 offset0:24 offset1:28
	s_waitcnt lgkmcnt(0)
	v_mfma_f32_16x16x4_f32 v[116:119], v120, v99, v[116:119]
	v_mfma_f32_16x16x4_f32 v[116:119], v121, v100, v[116:119]
	ds_read2_b32 v[120:121], v115 offset0:32 offset1:36
	s_waitcnt lgkmcnt(0)
	v_mfma_f32_16x16x4_f32 v[116:119], v120, v101, v[116:119]
	v_mfma_f32_16x16x4_f32 v[116:119], v121, v102, v[116:119]
	ds_read2_b32 v[120:121], v115 offset0:40 offset1:44
	s_waitcnt lgkmcnt(0)
	v_mfma_f32_16x16x4_f32 v[116:119], v120, v103, v[116:119]
	v_mfma_f32_16x16x4_f32 v[116:119], v121, v104, v[116:119]
	ds_read2_b32 v[120:121], v115 offset0:48 offset1:52
	s_waitcnt lgkmcnt(0)
	v_mfma_f32_16x16x4_f32 v[116:119], v120, v105, v[116:119]
	v_mfma_f32_16x16x4_f32 v[116:119], v121, v106, v[116:119]
	ds_read2_b32 v[120:121], v115 offset0:56 offset1:60
	s_waitcnt lgkmcnt(0)
	v_mfma_f32_16x16x4_f32 v[116:119], v120, v107, v[116:119]
	v_mfma_f32_16x16x4_f32 v[116:119], v121, v108, v[116:119]
	ds_read2_b32 v[120:121], v115 offset0:64 offset1:68
	s_waitcnt lgkmcnt(0)
	v_mfma_f32_16x16x4_f32 v[116:119], v120, v50, v[116:119]
	v_mfma_f32_16x16x4_f32 v[116:119], v121, v52, v[116:119]
	ds_read2_b32 v[120:121], v115 offset0:72 offset1:76
	s_waitcnt lgkmcnt(0)
	v_mfma_f32_16x16x4_f32 v[116:119], v120, v58, v[116:119]
	v_mfma_f32_16x16x4_f32 v[116:119], v121, v60, v[116:119]
	ds_read2_b32 v[120:121], v115 offset0:80 offset1:84
	s_waitcnt lgkmcnt(0)
	v_mfma_f32_16x16x4_f32 v[116:119], v120, v66, v[116:119]
	v_mfma_f32_16x16x4_f32 v[116:119], v121, v70, v[116:119]
	ds_read2_b32 v[120:121], v115 offset0:88 offset1:92
	s_waitcnt lgkmcnt(0)
	v_mfma_f32_16x16x4_f32 v[116:119], v120, v74, v[116:119]
	v_mfma_f32_16x16x4_f32 v[116:119], v121, v78, v[116:119]
	ds_read2_b32 v[120:121], v115 offset0:96 offset1:100
	s_waitcnt lgkmcnt(0)
	v_mfma_f32_16x16x4_f32 v[116:119], v120, v82, v[116:119]
	v_mfma_f32_16x16x4_f32 v[116:119], v121, v97, v[116:119]
	ds_read2_b32 v[120:121], v115 offset0:104 offset1:108
	s_waitcnt lgkmcnt(0)
	v_mfma_f32_16x16x4_f32 v[116:119], v120, v109, v[116:119]
	v_mfma_f32_16x16x4_f32 v[116:119], v121, v110, v[116:119]
	ds_read2_b32 v[120:121], v115 offset0:112 offset1:116
	s_waitcnt lgkmcnt(0)
	v_mfma_f32_16x16x4_f32 v[116:119], v120, v111, v[116:119]
	v_mfma_f32_16x16x4_f32 v[116:119], v121, v112, v[116:119]
	ds_read2_b32 v[120:121], v115 offset0:120 offset1:124
	v_add_u32_e32 v115, s14, v24
	s_add_i32 s14, s14, 16
	s_waitcnt lgkmcnt(0)
	v_mfma_f32_16x16x4_f32 v[116:119], v120, v113, v[116:119]
	v_cndmask_b32_e32 v120, v35, v115, vcc
	v_add_u32_e32 v35, -16, v35
	v_mfma_f32_16x16x4_f32 v[116:119], v121, v114, v[116:119]
	s_nop 9
	v_bfe_u32 v121, v116, 16, 1
	v_add3_u32 v116, v116, v121, s0
	v_ashrrev_i32_e32 v121, 31, v120
	v_lshl_add_u64 v[120:121], v[32:33], 0, v[120:121]
	v_lshlrev_b64 v[120:121], 10, v[120:121]
	v_lshl_add_u64 v[120:121], v[84:85], 0, v[120:121]
	global_store_short_d16_hi v[120:121], v116, off
	v_add_u32_e32 v116, 1, v115
	v_xad_u32 v120, v115, -2, v90
	v_cndmask_b32_e32 v116, v120, v116, vcc
	v_bfe_u32 v120, v117, 16, 1
	v_add3_u32 v120, v117, v120, s0
	v_ashrrev_i32_e32 v117, 31, v116
	v_lshl_add_u64 v[116:117], v[32:33], 0, v[116:117]
	v_lshlrev_b64 v[116:117], 10, v[116:117]
	v_lshl_add_u64 v[116:117], v[84:85], 0, v[116:117]
	global_store_short_d16_hi v[116:117], v120, off
	v_add_u32_e32 v116, 2, v115
	v_xad_u32 v117, v115, -3, v90
	v_cndmask_b32_e32 v116, v117, v116, vcc
	v_bfe_u32 v117, v118, 16, 1
	v_add3_u32 v118, v118, v117, s0
	v_ashrrev_i32_e32 v117, 31, v116
	v_lshl_add_u64 v[116:117], v[32:33], 0, v[116:117]
	v_lshlrev_b64 v[116:117], 10, v[116:117]
	v_lshl_add_u64 v[116:117], v[84:85], 0, v[116:117]
	global_store_short_d16_hi v[116:117], v118, off
	v_add_u32_e32 v116, 3, v115
	v_xad_u32 v115, v115, -4, v90
	v_cndmask_b32_e32 v116, v115, v116, vcc
	v_ashrrev_i32_e32 v117, 31, v116
	v_bfe_u32 v115, v119, 16, 1
	v_lshl_add_u64 v[116:117], v[32:33], 0, v[116:117]
	v_add3_u32 v115, v119, v115, s0
	v_lshlrev_b64 v[116:117], 10, v[116:117]
	v_cmp_eq_u32_e64 s[0:1], s15, v14
	v_lshl_add_u64 v[116:117], v[84:85], 0, v[116:117]
	s_or_b64 s[8:9], s[0:1], s[8:9]
	global_store_short_d16_hi v[116:117], v115, off
	s_andn2_b64 exec, exec, s[8:9]
	s_cbranch_execz .LBB0_828
